# strategy 4: one static s_setprio 1 for waves 4-7 over the attention unit loop (reset after it), on top of the fused P9
# baseline (speedup 1.0000x reference)
; #define LAS __attribute__((address_space(3)))
; __global__ void __launch_bounds__(NTHREADS, 2) fwd_megakernel(Args args) {
;     ...
;         constexpr int NUNITS = BATCH * 3 * 8 * 32;
;         const int per = (NUNITS + G - 1) / G;
;         const int u0 = vcu * per, u1 = (u0 + per < NUNITS) ? u0 + per : NUNITS;
;         { const v4u z = {0u, 0u, 0u, 0u}; for (int i = threadIdx.x; i < 8192; i += NTHREADS) *(LAS v4u*)(lds + 16 * i) = z; }
;         asm volatile("s_waitcnt lgkmcnt(0)" ::: "memory"); __builtin_amdgcn_s_barrier(); asm volatile("" ::: "memory");
;         AttnRegs R;
;         if (u0 < u1) { const AttnUnit un = attn_decode(u0);
;             if (un.n > 0) { attn_issue(R, un, un.n - 1, false, PROJ, BIAS2); attn_commit(R, un.n - 1, false, lds); }
;             attn_issue(R, un, un.n, true, PROJ, BIAS2); }
;         for (int uid = u0; uid < u1; ++uid) {
.LBB0_145:
	s_add_u32 s0, s40, 0x3fc00000
	s_addc_u32 s1, s41, 0
	s_add_u32 s33, s40, 0xbc00000
	s_addc_u32 s46, s41, 0
	s_add_u32 s47, s38, 0x8000000
	s_addc_u32 s64, s39, 0
	s_add_i32 s4, s59, s10
	s_or_b32 s4, s4, s6
	s_ashr_i32 s5, s4, 31
	s_lshl_b64 s[4:5], s[4:5], 20
	v_lshrrev_b32_e32 v1, 2, v178
	s_add_u32 s4, s18, s4
	v_and_b32_e32 v33, 0xf0, v1
	s_addc_u32 s5, s19, s5
	v_or_b32_e32 v1, v33, v92
	s_add_i32 s8, s9, s8
	v_add_lshl_u32 v80, s8, v1, 8
	v_mov_b32_e32 v81, 0
	v_lshl_add_u64 v[2:3], s[4:5], 0, v[80:81]
	s_add_i32 s4, s58, s10
	v_lshrrev_b32_e32 v1, 1, v178
	s_ashr_i32 s5, s4, 31
	v_and_b32_e32 v34, 24, v1
	s_lshl_b64 s[4:5], s[4:5], 20
	v_lshlrev_b32_e32 v80, 1, v34
	v_add_u32_e32 v0, s9, v0
	s_add_u32 s4, s18, s4
	v_lshl_add_u64 v[2:3], v[2:3], 0, v[80:81]
	v_lshl_or_b32 v80, v0, 7, v91
	s_addc_u32 s5, s19, s5
	v_lshl_add_u64 v[12:13], v[80:81], 1, s[4:5]
	s_mov_b32 s65, 0x18006000
	v_add_co_u32_e32 v0, vcc, s65, v12
	s_mov_b32 s66, 0xc006000
	s_nop 0
	v_addc_co_u32_e32 v1, vcc, 0, v13, vcc
	global_load_dwordx4 v[48:51], v[2:3], off offset:192
	global_load_dwordx4 v[52:55], v[2:3], off offset:128
	global_load_dwordx4 v[56:59], v[2:3], off offset:64
	global_load_dwordx4 v[60:63], v[2:3], off
	v_add_co_u32_e32 v2, vcc, s66, v12
	s_mov_b32 s67, 0x18004000
	s_nop 0
	v_addc_co_u32_e32 v3, vcc, 0, v13, vcc
	v_add_co_u32_e32 v4, vcc, s67, v12
	s_mov_b32 s68, 0xc004000
	s_nop 0
	v_addc_co_u32_e32 v5, vcc, 0, v13, vcc
	v_add_co_u32_e32 v6, vcc, s68, v12
	s_mov_b32 s69, 0x18002000
	s_nop 0
	v_addc_co_u32_e32 v7, vcc, 0, v13, vcc
	v_add_co_u32_e32 v8, vcc, s69, v12
	s_mov_b32 s70, 0xc002000
	s_nop 0
	v_addc_co_u32_e32 v9, vcc, 0, v13, vcc
	s_lshl_b32 s4, s7, 3
	v_add_co_u32_e32 v10, vcc, s70, v12
	s_or_b32 s4, s4, s6
	s_movk_i32 s5, 0xc0
	v_addc_co_u32_e32 v11, vcc, 0, v13, vcc
	s_brev_b32 s71, 24
	s_mul_i32 s6, s4, 0xc0
	v_cmp_gt_u32_e64 s[4:5], s5, v178
	v_add_co_u32_e32 v14, vcc, s71, v12
	s_nop 0
	v_cndmask_b32_e64 v95, 0, v178, s[4:5]
	v_addc_co_u32_e32 v15, vcc, 0, v13, vcc
	s_brev_b32 s72, 48
	v_add_u32_e32 v36, s6, v95
	v_add_co_u32_e32 v12, vcc, s72, v12
	v_ashrrev_i32_e32 v37, 31, v36
	s_nop 0
	v_addc_co_u32_e32 v13, vcc, 0, v13, vcc
	v_lshl_add_u64 v[36:37], v[36:37], 2, s[56:57]
	global_load_dwordx4 v[28:31], v[0:1], off
	s_nop 0
	global_load_dwordx4 v[0:3], v[2:3], off
	s_nop 0
	global_load_dwordx4 v[16:19], v[4:5], off
	s_nop 0
	global_load_dwordx4 v[4:7], v[6:7], off
	s_nop 0
	global_load_dwordx4 v[20:23], v[8:9], off
	s_nop 0
	global_load_dwordx4 v[8:11], v[10:11], off
	s_nop 0
	global_load_dwordx4 v[24:27], v[14:15], off
	s_nop 0
	global_load_dwordx4 v[12:15], v[12:13], off
	v_lshlrev_b32_e32 v35, 2, v178
	global_load_dword v125, v[36:37], off
	s_add_i32 s6, 0, 0x20000
	v_add_u32_e32 v97, s6, v35
	v_and_b32_e32 v102, 12, v35
	v_lshrrev_b32_e32 v35, 1, v92
	v_bfe_u32 v99, v178, 4, 2
	v_and_b32_e32 v35, 2, v35
	v_or_b32_e32 v98, v33, v92
	v_lshrrev_b32_e32 v33, 2, v92
	v_bitop3_b32 v36, v35, v99, v102 bitop3:0x36
	v_or_b32_e32 v104, 4, v99
	v_lshlrev_b32_e32 v100, 3, v33
	v_lshlrev_b32_e32 v103, 4, v36
	v_bitop3_b32 v36, v35, v104, v102 bitop3:0x36
	v_or_b32_e32 v106, 8, v99
	v_or_b32_e32 v108, 12, v99
	v_lshl_or_b32 v111, v99, 3, v33
	v_lshlrev_b32_e32 v33, 1, v90
	v_lshlrev_b32_e32 v105, 4, v36
	v_bitop3_b32 v36, v35, v106, v102 bitop3:0x36
	v_bitop3_b32 v35, v35, v108, v102 bitop3:0x36
	v_and_b32_e32 v113, 12, v178
	v_and_b32_e32 v33, 2, v33
	v_lshlrev_b32_e32 v109, 4, v35
	v_bfe_u32 v112, v178, 1, 1
	v_or_b32_e32 v35, v33, v113
	v_and_b32_e32 v114, 8, v32
	v_or_b32_e32 v32, v35, v112
	v_or_b32_e32 v116, 2, v112
	v_lshlrev_b32_e32 v115, 4, v32
	v_bitop3_b32 v32, v33, v116, v113 bitop3:0x36
	v_or_b32_e32 v118, 4, v112
	v_lshlrev_b32_e32 v117, 4, v32
	v_bitop3_b32 v32, v33, v118, v113 bitop3:0x36
	v_or_b32_e32 v120, 6, v112
	v_lshlrev_b32_e32 v119, 4, v32
	v_bitop3_b32 v32, v33, v120, v113 bitop3:0x36
	v_or_b32_e32 v122, 8, v112
	v_lshlrev_b32_e32 v121, 4, v32
	v_bitop3_b32 v32, v33, v122, v113 bitop3:0x36
	v_or_b32_e32 v124, 10, v112
	v_lshlrev_b32_e32 v123, 4, v32
	v_bitop3_b32 v32, v33, v124, v113 bitop3:0x36
	v_or_b32_e32 v127, 12, v112
	v_lshlrev_b32_e32 v126, 4, v32
	v_bitop3_b32 v32, v33, v127, v113 bitop3:0x36
	v_or_b32_e32 v129, 14, v112
	v_lshlrev_b32_e32 v128, 4, v32
	v_bitop3_b32 v32, v33, v129, v113 bitop3:0x36
	v_lshlrev_b32_e32 v130, 4, v32
	v_lshlrev_b32_e32 v32, 2, v99
	v_lshlrev_b32_e32 v84, 1, v32
	v_mbcnt_lo_u32_b32 v32, -1, 0
	s_mov_b32 s9, 0
	v_or_b32_e32 v96, 0x4000, v93
	v_and_b32_e32 v101, 3, v178
	v_lshlrev_b32_e32 v107, 4, v36
	v_lshl_add_u32 v110, v99, 5, s6
	v_cmp_eq_u32_e64 s[6:7], 0, v99
	s_add_i32 s73, 0, 0x10000
	v_lshlrev_b32_e32 v82, 1, v34
	s_mov_b32 s74, 0xf149f2ca
	v_mov_b32_e32 v131, 0xf149f2ca
	v_mbcnt_hi_u32_b32 v132, -1, v32
	v_readfirstlane_b32 s32, v178
	s_nop 3
	s_lshr_b32 s32, s32, 6
	s_cmp_ge_u32 s32, 4
	s_cbranch_scc0 .Lp2_prio_done
	s_setprio 1

; __device__ __forceinline__ unsigned xb_add(unsigned* p, unsigned v) { return __hip_atomic_fetch_add(p, v, __ATOMIC_RELAXED, __HIP_MEMORY_SCOPE_AGENT); }
; __device__ __forceinline__ void xcd_barrier(const XcdBarrier& b) {
;     asm volatile("s_waitcnt vmcnt(0)" ::: "memory");
;     __syncthreads();
;     if (threadIdx.x == 0) {
;         unsigned* bar = b.bar;
;         __builtin_amdgcn_s_waitcnt(0);
;         unsigned nloc = b.st[0], nx = b.st[1];
;         if (nloc == 0u) { xcd_barrier_complete(bar, b.x, nloc, nx); b.st[0] = nloc; b.st[1] = nx; }
;         const unsigned old = xb_add(&bar[XB_XSUB(b.x)], 1u);
; __global__ void __launch_bounds__(NTHREADS, 2) fwd_megakernel(Args args) {
;     ...
;     xcd_barrier(xbar);
.LBB0_153:
	s_setprio 0
	s_waitcnt vmcnt(0)
	s_waitcnt lgkmcnt(0)
	s_barrier
	s_mov_b64 s[4:5], exec
	v_readlane_b32 s0, v244, 4
	v_readlane_b32 s1, v244, 5
	s_and_b64 s[0:1], s[4:5], s[0:1]
	s_mov_b64 exec, s[0:1]
	s_cbranch_execz .LBB0_206
	s_add_i32 s0, 0, 0x22400
	v_mov_b32_e32 v0, s0
	s_waitcnt vmcnt(0) expcnt(0) lgkmcnt(0)
	ds_read_b32 v2, v0
	s_add_i32 s0, 0, 0x22404
	v_mov_b32_e32 v0, s0
	ds_read_b32 v0, v0
	s_waitcnt lgkmcnt(1)
	v_cmp_ne_u32_e32 vcc, 0, v2
	s_cbranch_vccnz .LBB0_170
	s_add_u32 s6, s40, 0x1000
	s_addc_u32 s7, s41, 0
	s_add_u32 s8, s40, 0x1100
	s_addc_u32 s9, s41, 0
	s_add_u32 s10, s40, 0x1200
	s_addc_u32 s11, s41, 0
	s_mul_i32 s0, s43, s95
	s_add_u32 s56, s40, 0x1300
	s_mul_i32 s0, s0, s42
	s_addc_u32 s57, s41, 0
	s_mov_b32 s1, 1
	v_mov_b32_e32 v16, 0
	s_branch .LBB0_157
